# phase-0 adaLN GEMV K loop rewritten: weight rows of three iterations (24 loads/wave) in flight instead of 8; f32 FMA accumulation in k order
# speedup vs baseline: 1.0231x; 1.0027x over previous
.LBB0_11:
	s_mul_hi_i32 s0, s8, 0x38e38e39
	s_lshr_b32 s1, s0, 31
	s_ashr_i32 s0, s0, 5
	s_add_i32 s12, s0, s1
	s_mul_i32 s0, s12, 0x2400
	s_sub_i32 s0, s9, s0
	s_ashr_i32 s1, s0, 31
	s_mul_i32 s7, s12, 0x2400000
	s_lshl_b64 s[0:1], s[0:1], 2
	s_mul_hi_i32 s6, s12, 0x2400000
	s_add_u32 s0, s7, s0
	s_addc_u32 s1, s6, s1
	v_lshl_add_u64 v[28:29], v[22:23], 0, s[0:1]
	s_mov_b64 s[6:7], 0
	v_mov_b32_e32 v37, v36
	v_mov_b32_e32 v38, v1
	v_mov_b32_e32 v24, 0
	v_mov_b32_e32 v25, v17
	v_mov_b32_e32 v26, 0
	v_mov_b32_e32 v27, v17
	v_mov_b32_e32 v30, 0
	v_mov_b32_e32 v31, v17
	v_mov_b32_e32 v32, 0
	v_mov_b32_e32 v33, v17
	v_readfirstlane_b32 s36, v28
	v_readfirstlane_b32 s37, v29
	s_sub_u32 s36, s36, 0x3f000
	s_subb_u32 s37, s37, 0
	global_load_dword v40, v16, s[36:37] nt
	s_add_u32 s36, s36, 0x9000
	s_addc_u32 s37, s37, 0
	global_load_dword v41, v16, s[36:37] nt
	s_add_u32 s36, s36, 0x9000
	s_addc_u32 s37, s37, 0
	global_load_dword v42, v16, s[36:37] nt
	s_add_u32 s36, s36, 0x9000
	s_addc_u32 s37, s37, 0
	global_load_dword v43, v16, s[36:37] nt
	s_add_u32 s36, s36, 0x9000
	s_addc_u32 s37, s37, 0
	global_load_dword v44, v16, s[36:37] nt
	s_add_u32 s36, s36, 0x9000
	s_addc_u32 s37, s37, 0
	global_load_dword v45, v16, s[36:37] nt
	s_add_u32 s36, s36, 0x9000
	s_addc_u32 s37, s37, 0
	global_load_dword v46, v16, s[36:37] nt
	s_add_u32 s36, s36, 0x9000
	s_addc_u32 s37, s37, 0
	global_load_dword v47, v16, s[36:37] nt
	s_add_u32 s36, s36, 0x9000
	s_addc_u32 s37, s37, 0
	global_load_dword v48, v16, s[36:37] nt
	s_add_u32 s36, s36, 0x9000
	s_addc_u32 s37, s37, 0
	global_load_dword v49, v16, s[36:37] nt
	s_add_u32 s36, s36, 0x9000
	s_addc_u32 s37, s37, 0
	global_load_dword v50, v16, s[36:37] nt
	s_add_u32 s36, s36, 0x9000
	s_addc_u32 s37, s37, 0
	global_load_dword v51, v16, s[36:37] nt
	s_add_u32 s36, s36, 0x9000
	s_addc_u32 s37, s37, 0
	global_load_dword v52, v16, s[36:37] nt
	s_add_u32 s36, s36, 0x9000
	s_addc_u32 s37, s37, 0
	global_load_dword v53, v16, s[36:37] nt
	s_add_u32 s36, s36, 0x9000
	s_addc_u32 s37, s37, 0
	global_load_dword v54, v16, s[36:37] nt
	s_add_u32 s36, s36, 0x9000
	s_addc_u32 s37, s37, 0
	global_load_dword v55, v16, s[36:37] nt
	s_add_u32 s36, s36, 0x9000
	s_addc_u32 s37, s37, 0
	global_load_dword v56, v16, s[36:37] nt
	s_add_u32 s36, s36, 0x9000
	s_addc_u32 s37, s37, 0
	global_load_dword v57, v16, s[36:37] nt
	s_add_u32 s36, s36, 0x9000
	s_addc_u32 s37, s37, 0
	global_load_dword v58, v16, s[36:37] nt
	s_add_u32 s36, s36, 0x9000
	s_addc_u32 s37, s37, 0
	global_load_dword v59, v16, s[36:37] nt
	s_add_u32 s36, s36, 0x9000
	s_addc_u32 s37, s37, 0
	global_load_dword v60, v16, s[36:37] nt
	s_add_u32 s36, s36, 0x9000
	s_addc_u32 s37, s37, 0
	global_load_dword v61, v16, s[36:37] nt
	s_add_u32 s36, s36, 0x9000
	s_addc_u32 s37, s37, 0
	global_load_dword v62, v16, s[36:37] nt
	s_add_u32 s36, s36, 0x9000
	s_addc_u32 s37, s37, 0
	global_load_dword v63, v16, s[36:37] nt
	s_add_u32 s36, s36, 0x9000
	s_addc_u32 s37, s37, 0
	s_mov_b32 s38, 7
.Lp0_loop:
	global_load_dword v64, v16, s[36:37] nt
	s_add_u32 s36, s36, 0x9000
	s_addc_u32 s37, s37, 0
	global_load_dword v65, v16, s[36:37] nt
	s_add_u32 s36, s36, 0x9000
	s_addc_u32 s37, s37, 0
	global_load_dword v66, v16, s[36:37] nt
	s_add_u32 s36, s36, 0x9000
	s_addc_u32 s37, s37, 0
	global_load_dword v67, v16, s[36:37] nt
	s_add_u32 s36, s36, 0x9000
	s_addc_u32 s37, s37, 0
	global_load_dword v68, v16, s[36:37] nt
	s_add_u32 s36, s36, 0x9000
	s_addc_u32 s37, s37, 0
	global_load_dword v69, v16, s[36:37] nt
	s_add_u32 s36, s36, 0x9000
	s_addc_u32 s37, s37, 0
	global_load_dword v70, v16, s[36:37] nt
	s_add_u32 s36, s36, 0x9000
	s_addc_u32 s37, s37, 0
	global_load_dword v71, v16, s[36:37] nt
	s_add_u32 s36, s36, 0x9000
	s_addc_u32 s37, s37, 0
	ds_read_b128 v[72:75], v37 offset:0
	ds_read_b128 v[76:79], v37 offset:16
	ds_read_b128 v[80:83], v37 offset:4096
	ds_read_b128 v[84:87], v37 offset:4112
	ds_read_b128 v[88:91], v37 offset:8192
	ds_read_b128 v[92:95], v37 offset:8208
	ds_read_b128 v[96:99], v37 offset:12288
	ds_read_b128 v[100:103], v37 offset:12304
	ds_read_b128 v[104:107], v37 offset:16384
	ds_read_b128 v[108:111], v37 offset:16400
	ds_read_b128 v[112:115], v37 offset:20480
	ds_read_b128 v[116:119], v37 offset:20496
	ds_read_b128 v[120:123], v37 offset:24576
	ds_read_b128 v[124:127], v37 offset:24592
	ds_read_b128 v[128:131], v37 offset:28672
	ds_read_b128 v[132:135], v37 offset:28688
	s_waitcnt vmcnt(24) lgkmcnt(0)
	v_fmac_f32_e32 v26, v72, v40
	v_fmac_f32_e32 v27, v80, v40
	v_fmac_f32_e32 v30, v88, v40
	v_fmac_f32_e32 v31, v96, v40
	v_fmac_f32_e32 v32, v104, v40
	v_fmac_f32_e32 v33, v112, v40
	v_fmac_f32_e32 v24, v120, v40
	v_fmac_f32_e32 v25, v128, v40
	v_fmac_f32_e32 v26, v73, v41
	v_fmac_f32_e32 v27, v81, v41
	v_fmac_f32_e32 v30, v89, v41
	v_fmac_f32_e32 v31, v97, v41
	v_fmac_f32_e32 v32, v105, v41
	v_fmac_f32_e32 v33, v113, v41
	v_fmac_f32_e32 v24, v121, v41
	v_fmac_f32_e32 v25, v129, v41
	v_fmac_f32_e32 v26, v74, v42
	v_fmac_f32_e32 v27, v82, v42
	v_fmac_f32_e32 v30, v90, v42
	v_fmac_f32_e32 v31, v98, v42
	v_fmac_f32_e32 v32, v106, v42
	v_fmac_f32_e32 v33, v114, v42
	v_fmac_f32_e32 v24, v122, v42
	v_fmac_f32_e32 v25, v130, v42
	v_fmac_f32_e32 v26, v75, v43
	v_fmac_f32_e32 v27, v83, v43
	v_fmac_f32_e32 v30, v91, v43
	v_fmac_f32_e32 v31, v99, v43
	v_fmac_f32_e32 v32, v107, v43
	v_fmac_f32_e32 v33, v115, v43
	v_fmac_f32_e32 v24, v123, v43
	v_fmac_f32_e32 v25, v131, v43
	v_fmac_f32_e32 v26, v76, v44
	v_fmac_f32_e32 v27, v84, v44
	v_fmac_f32_e32 v30, v92, v44
	v_fmac_f32_e32 v31, v100, v44
	v_fmac_f32_e32 v32, v108, v44
	v_fmac_f32_e32 v33, v116, v44
	v_fmac_f32_e32 v24, v124, v44
	v_fmac_f32_e32 v25, v132, v44
	v_fmac_f32_e32 v26, v77, v45
	v_fmac_f32_e32 v27, v85, v45
	v_fmac_f32_e32 v30, v93, v45
	v_fmac_f32_e32 v31, v101, v45
	v_fmac_f32_e32 v32, v109, v45
	v_fmac_f32_e32 v33, v117, v45
	v_fmac_f32_e32 v24, v125, v45
	v_fmac_f32_e32 v25, v133, v45
	v_fmac_f32_e32 v26, v78, v46
	v_fmac_f32_e32 v27, v86, v46
	v_fmac_f32_e32 v30, v94, v46
	v_fmac_f32_e32 v31, v102, v46
	v_fmac_f32_e32 v32, v110, v46
	v_fmac_f32_e32 v33, v118, v46
	v_fmac_f32_e32 v24, v126, v46
	v_fmac_f32_e32 v25, v134, v46
	v_fmac_f32_e32 v26, v79, v47
	v_fmac_f32_e32 v27, v87, v47
	v_fmac_f32_e32 v30, v95, v47
	v_fmac_f32_e32 v31, v103, v47
	v_fmac_f32_e32 v32, v111, v47
	v_fmac_f32_e32 v33, v119, v47
	v_fmac_f32_e32 v24, v127, v47
	v_fmac_f32_e32 v25, v135, v47
	global_load_dword v40, v16, s[36:37] nt
	s_add_u32 s36, s36, 0x9000
	s_addc_u32 s37, s37, 0
	global_load_dword v41, v16, s[36:37] nt
	s_add_u32 s36, s36, 0x9000
	s_addc_u32 s37, s37, 0
	global_load_dword v42, v16, s[36:37] nt
	s_add_u32 s36, s36, 0x9000
	s_addc_u32 s37, s37, 0
	global_load_dword v43, v16, s[36:37] nt
	s_add_u32 s36, s36, 0x9000
	s_addc_u32 s37, s37, 0
	global_load_dword v44, v16, s[36:37] nt
	s_add_u32 s36, s36, 0x9000
	s_addc_u32 s37, s37, 0
	global_load_dword v45, v16, s[36:37] nt
	s_add_u32 s36, s36, 0x9000
	s_addc_u32 s37, s37, 0
	global_load_dword v46, v16, s[36:37] nt
	s_add_u32 s36, s36, 0x9000
	s_addc_u32 s37, s37, 0
	global_load_dword v47, v16, s[36:37] nt
	s_add_u32 s36, s36, 0x9000
	s_addc_u32 s37, s37, 0
	ds_read_b128 v[72:75], v37 offset:32
	ds_read_b128 v[76:79], v37 offset:48
	ds_read_b128 v[80:83], v37 offset:4128
	ds_read_b128 v[84:87], v37 offset:4144
	ds_read_b128 v[88:91], v37 offset:8224
	ds_read_b128 v[92:95], v37 offset:8240
	ds_read_b128 v[96:99], v37 offset:12320
	ds_read_b128 v[100:103], v37 offset:12336
	ds_read_b128 v[104:107], v37 offset:16416
	ds_read_b128 v[108:111], v37 offset:16432
	ds_read_b128 v[112:115], v37 offset:20512
	ds_read_b128 v[116:119], v37 offset:20528
	ds_read_b128 v[120:123], v37 offset:24608
	ds_read_b128 v[124:127], v37 offset:24624
	ds_read_b128 v[128:131], v37 offset:28704
	ds_read_b128 v[132:135], v37 offset:28720
	s_waitcnt vmcnt(24) lgkmcnt(0)
	v_fmac_f32_e32 v26, v72, v48
	v_fmac_f32_e32 v27, v80, v48
	v_fmac_f32_e32 v30, v88, v48
	v_fmac_f32_e32 v31, v96, v48
	v_fmac_f32_e32 v32, v104, v48
	v_fmac_f32_e32 v33, v112, v48
	v_fmac_f32_e32 v24, v120, v48
	v_fmac_f32_e32 v25, v128, v48
	v_fmac_f32_e32 v26, v73, v49
	v_fmac_f32_e32 v27, v81, v49
	v_fmac_f32_e32 v30, v89, v49
	v_fmac_f32_e32 v31, v97, v49
	v_fmac_f32_e32 v32, v105, v49
	v_fmac_f32_e32 v33, v113, v49
	v_fmac_f32_e32 v24, v121, v49
	v_fmac_f32_e32 v25, v129, v49
	v_fmac_f32_e32 v26, v74, v50
	v_fmac_f32_e32 v27, v82, v50
	v_fmac_f32_e32 v30, v90, v50
	v_fmac_f32_e32 v31, v98, v50
	v_fmac_f32_e32 v32, v106, v50
	v_fmac_f32_e32 v33, v114, v50
	v_fmac_f32_e32 v24, v122, v50
	v_fmac_f32_e32 v25, v130, v50
	v_fmac_f32_e32 v26, v75, v51
	v_fmac_f32_e32 v27, v83, v51
	v_fmac_f32_e32 v30, v91, v51
	v_fmac_f32_e32 v31, v99, v51
	v_fmac_f32_e32 v32, v107, v51
	v_fmac_f32_e32 v33, v115, v51
	v_fmac_f32_e32 v24, v123, v51
	v_fmac_f32_e32 v25, v131, v51
	v_fmac_f32_e32 v26, v76, v52
	v_fmac_f32_e32 v27, v84, v52
	v_fmac_f32_e32 v30, v92, v52
	v_fmac_f32_e32 v31, v100, v52
	v_fmac_f32_e32 v32, v108, v52
	v_fmac_f32_e32 v33, v116, v52
	v_fmac_f32_e32 v24, v124, v52
	v_fmac_f32_e32 v25, v132, v52
	v_fmac_f32_e32 v26, v77, v53
	v_fmac_f32_e32 v27, v85, v53
	v_fmac_f32_e32 v30, v93, v53
	v_fmac_f32_e32 v31, v101, v53
	v_fmac_f32_e32 v32, v109, v53
	v_fmac_f32_e32 v33, v117, v53
	v_fmac_f32_e32 v24, v125, v53
	v_fmac_f32_e32 v25, v133, v53
	v_fmac_f32_e32 v26, v78, v54
	v_fmac_f32_e32 v27, v86, v54
	v_fmac_f32_e32 v30, v94, v54
	v_fmac_f32_e32 v31, v102, v54
	v_fmac_f32_e32 v32, v110, v54
	v_fmac_f32_e32 v33, v118, v54
	v_fmac_f32_e32 v24, v126, v54
	v_fmac_f32_e32 v25, v134, v54
	v_fmac_f32_e32 v26, v79, v55
	v_fmac_f32_e32 v27, v87, v55
	v_fmac_f32_e32 v30, v95, v55
	v_fmac_f32_e32 v31, v103, v55
	v_fmac_f32_e32 v32, v111, v55
	v_fmac_f32_e32 v33, v119, v55
	v_fmac_f32_e32 v24, v127, v55
	v_fmac_f32_e32 v25, v135, v55
	global_load_dword v48, v16, s[36:37] nt
	s_add_u32 s36, s36, 0x9000
	s_addc_u32 s37, s37, 0
	global_load_dword v49, v16, s[36:37] nt
	s_add_u32 s36, s36, 0x9000
	s_addc_u32 s37, s37, 0
	global_load_dword v50, v16, s[36:37] nt
	s_add_u32 s36, s36, 0x9000
	s_addc_u32 s37, s37, 0
	global_load_dword v51, v16, s[36:37] nt
	s_add_u32 s36, s36, 0x9000
	s_addc_u32 s37, s37, 0
	global_load_dword v52, v16, s[36:37] nt
	s_add_u32 s36, s36, 0x9000
	s_addc_u32 s37, s37, 0
	global_load_dword v53, v16, s[36:37] nt
	s_add_u32 s36, s36, 0x9000
	s_addc_u32 s37, s37, 0
	global_load_dword v54, v16, s[36:37] nt
	s_add_u32 s36, s36, 0x9000
	s_addc_u32 s37, s37, 0
	global_load_dword v55, v16, s[36:37] nt
	s_add_u32 s36, s36, 0x9000
	s_addc_u32 s37, s37, 0
	ds_read_b128 v[72:75], v37 offset:64
	ds_read_b128 v[76:79], v37 offset:80
	ds_read_b128 v[80:83], v37 offset:4160
	ds_read_b128 v[84:87], v37 offset:4176
	ds_read_b128 v[88:91], v37 offset:8256
	ds_read_b128 v[92:95], v37 offset:8272
	ds_read_b128 v[96:99], v37 offset:12352
	ds_read_b128 v[100:103], v37 offset:12368
	ds_read_b128 v[104:107], v37 offset:16448
	ds_read_b128 v[108:111], v37 offset:16464
	ds_read_b128 v[112:115], v37 offset:20544
	ds_read_b128 v[116:119], v37 offset:20560
	ds_read_b128 v[120:123], v37 offset:24640
	ds_read_b128 v[124:127], v37 offset:24656
	ds_read_b128 v[128:131], v37 offset:28736
	ds_read_b128 v[132:135], v37 offset:28752
	s_waitcnt vmcnt(24) lgkmcnt(0)
	v_fmac_f32_e32 v26, v72, v56
	v_fmac_f32_e32 v27, v80, v56
	v_fmac_f32_e32 v30, v88, v56
	v_fmac_f32_e32 v31, v96, v56
	v_fmac_f32_e32 v32, v104, v56
	v_fmac_f32_e32 v33, v112, v56
	v_fmac_f32_e32 v24, v120, v56
	v_fmac_f32_e32 v25, v128, v56
	v_fmac_f32_e32 v26, v73, v57
	v_fmac_f32_e32 v27, v81, v57
	v_fmac_f32_e32 v30, v89, v57
	v_fmac_f32_e32 v31, v97, v57
	v_fmac_f32_e32 v32, v105, v57
	v_fmac_f32_e32 v33, v113, v57
	v_fmac_f32_e32 v24, v121, v57
	v_fmac_f32_e32 v25, v129, v57
	v_fmac_f32_e32 v26, v74, v58
	v_fmac_f32_e32 v27, v82, v58
	v_fmac_f32_e32 v30, v90, v58
	v_fmac_f32_e32 v31, v98, v58
	v_fmac_f32_e32 v32, v106, v58
	v_fmac_f32_e32 v33, v114, v58
	v_fmac_f32_e32 v24, v122, v58
	v_fmac_f32_e32 v25, v130, v58
	v_fmac_f32_e32 v26, v75, v59
	v_fmac_f32_e32 v27, v83, v59
	v_fmac_f32_e32 v30, v91, v59
	v_fmac_f32_e32 v31, v99, v59
	v_fmac_f32_e32 v32, v107, v59
	v_fmac_f32_e32 v33, v115, v59
	v_fmac_f32_e32 v24, v123, v59
	v_fmac_f32_e32 v25, v131, v59
	v_fmac_f32_e32 v26, v76, v60
	v_fmac_f32_e32 v27, v84, v60
	v_fmac_f32_e32 v30, v92, v60
	v_fmac_f32_e32 v31, v100, v60
	v_fmac_f32_e32 v32, v108, v60
	v_fmac_f32_e32 v33, v116, v60
	v_fmac_f32_e32 v24, v124, v60
	v_fmac_f32_e32 v25, v132, v60
	v_fmac_f32_e32 v26, v77, v61
	v_fmac_f32_e32 v27, v85, v61
	v_fmac_f32_e32 v30, v93, v61
	v_fmac_f32_e32 v31, v101, v61
	v_fmac_f32_e32 v32, v109, v61
	v_fmac_f32_e32 v33, v117, v61
	v_fmac_f32_e32 v24, v125, v61
	v_fmac_f32_e32 v25, v133, v61
	v_fmac_f32_e32 v26, v78, v62
	v_fmac_f32_e32 v27, v86, v62
	v_fmac_f32_e32 v30, v94, v62
	v_fmac_f32_e32 v31, v102, v62
	v_fmac_f32_e32 v32, v110, v62
	v_fmac_f32_e32 v33, v118, v62
	v_fmac_f32_e32 v24, v126, v62
	v_fmac_f32_e32 v25, v134, v62
	v_fmac_f32_e32 v26, v79, v63
	v_fmac_f32_e32 v27, v87, v63
	v_fmac_f32_e32 v30, v95, v63
	v_fmac_f32_e32 v31, v103, v63
	v_fmac_f32_e32 v32, v111, v63
	v_fmac_f32_e32 v33, v119, v63
	v_fmac_f32_e32 v24, v127, v63
	v_fmac_f32_e32 v25, v135, v63
	global_load_dword v56, v16, s[36:37] nt
	s_add_u32 s36, s36, 0x9000
	s_addc_u32 s37, s37, 0
	global_load_dword v57, v16, s[36:37] nt
	s_add_u32 s36, s36, 0x9000
	s_addc_u32 s37, s37, 0
	global_load_dword v58, v16, s[36:37] nt
	s_add_u32 s36, s36, 0x9000
	s_addc_u32 s37, s37, 0
	global_load_dword v59, v16, s[36:37] nt
	s_add_u32 s36, s36, 0x9000
	s_addc_u32 s37, s37, 0
	global_load_dword v60, v16, s[36:37] nt
	s_add_u32 s36, s36, 0x9000
	s_addc_u32 s37, s37, 0
	global_load_dword v61, v16, s[36:37] nt
	s_add_u32 s36, s36, 0x9000
	s_addc_u32 s37, s37, 0
	global_load_dword v62, v16, s[36:37] nt
	s_add_u32 s36, s36, 0x9000
	s_addc_u32 s37, s37, 0
	global_load_dword v63, v16, s[36:37] nt
	s_add_u32 s36, s36, 0x9000
	s_addc_u32 s37, s37, 0
	ds_read_b128 v[72:75], v37 offset:96
	ds_read_b128 v[76:79], v37 offset:112
	ds_read_b128 v[80:83], v37 offset:4192
	ds_read_b128 v[84:87], v37 offset:4208
	ds_read_b128 v[88:91], v37 offset:8288
	ds_read_b128 v[92:95], v37 offset:8304
	ds_read_b128 v[96:99], v37 offset:12384
	ds_read_b128 v[100:103], v37 offset:12400
	ds_read_b128 v[104:107], v37 offset:16480
	ds_read_b128 v[108:111], v37 offset:16496
	ds_read_b128 v[112:115], v37 offset:20576
	ds_read_b128 v[116:119], v37 offset:20592
	ds_read_b128 v[120:123], v37 offset:24672
	ds_read_b128 v[124:127], v37 offset:24688
	ds_read_b128 v[128:131], v37 offset:28768
	ds_read_b128 v[132:135], v37 offset:28784
	s_waitcnt vmcnt(24) lgkmcnt(0)
	v_fmac_f32_e32 v26, v72, v64
	v_fmac_f32_e32 v27, v80, v64
	v_fmac_f32_e32 v30, v88, v64
	v_fmac_f32_e32 v31, v96, v64
	v_fmac_f32_e32 v32, v104, v64
	v_fmac_f32_e32 v33, v112, v64
	v_fmac_f32_e32 v24, v120, v64
	v_fmac_f32_e32 v25, v128, v64
	v_fmac_f32_e32 v26, v73, v65
	v_fmac_f32_e32 v27, v81, v65
	v_fmac_f32_e32 v30, v89, v65
	v_fmac_f32_e32 v31, v97, v65
	v_fmac_f32_e32 v32, v105, v65
	v_fmac_f32_e32 v33, v113, v65
	v_fmac_f32_e32 v24, v121, v65
	v_fmac_f32_e32 v25, v129, v65
	v_fmac_f32_e32 v26, v74, v66
	v_fmac_f32_e32 v27, v82, v66
	v_fmac_f32_e32 v30, v90, v66
	v_fmac_f32_e32 v31, v98, v66
	v_fmac_f32_e32 v32, v106, v66
	v_fmac_f32_e32 v33, v114, v66
	v_fmac_f32_e32 v24, v122, v66
	v_fmac_f32_e32 v25, v130, v66
	v_fmac_f32_e32 v26, v75, v67
	v_fmac_f32_e32 v27, v83, v67
	v_fmac_f32_e32 v30, v91, v67
	v_fmac_f32_e32 v31, v99, v67
	v_fmac_f32_e32 v32, v107, v67
	v_fmac_f32_e32 v33, v115, v67
	v_fmac_f32_e32 v24, v123, v67
	v_fmac_f32_e32 v25, v131, v67
	v_fmac_f32_e32 v26, v76, v68
	v_fmac_f32_e32 v27, v84, v68
	v_fmac_f32_e32 v30, v92, v68
	v_fmac_f32_e32 v31, v100, v68
	v_fmac_f32_e32 v32, v108, v68
	v_fmac_f32_e32 v33, v116, v68
	v_fmac_f32_e32 v24, v124, v68
	v_fmac_f32_e32 v25, v132, v68
	v_fmac_f32_e32 v26, v77, v69
	v_fmac_f32_e32 v27, v85, v69
	v_fmac_f32_e32 v30, v93, v69
	v_fmac_f32_e32 v31, v101, v69
	v_fmac_f32_e32 v32, v109, v69
	v_fmac_f32_e32 v33, v117, v69
	v_fmac_f32_e32 v24, v125, v69
	v_fmac_f32_e32 v25, v133, v69
	v_fmac_f32_e32 v26, v78, v70
	v_fmac_f32_e32 v27, v86, v70
	v_fmac_f32_e32 v30, v94, v70
	v_fmac_f32_e32 v31, v102, v70
	v_fmac_f32_e32 v32, v110, v70
	v_fmac_f32_e32 v33, v118, v70
	v_fmac_f32_e32 v24, v126, v70
	v_fmac_f32_e32 v25, v134, v70
	v_fmac_f32_e32 v26, v79, v71
	v_fmac_f32_e32 v27, v87, v71
	v_fmac_f32_e32 v30, v95, v71
	v_fmac_f32_e32 v31, v103, v71
	v_fmac_f32_e32 v32, v111, v71
	v_fmac_f32_e32 v33, v119, v71
	v_fmac_f32_e32 v24, v127, v71
	v_fmac_f32_e32 v25, v135, v71
	v_add_u32_e32 v37, 0x80, v37
	s_sub_u32 s38, s38, 1
	s_cmp_lg_u32 s38, 0
	s_cbranch_scc1 .Lp0_loop
	global_load_dword v64, v16, s[36:37] nt
	s_add_u32 s36, s36, 0x9000
	s_addc_u32 s37, s37, 0
	global_load_dword v65, v16, s[36:37] nt
	s_add_u32 s36, s36, 0x9000
	s_addc_u32 s37, s37, 0
	global_load_dword v66, v16, s[36:37] nt
	s_add_u32 s36, s36, 0x9000
	s_addc_u32 s37, s37, 0
	global_load_dword v67, v16, s[36:37] nt
	s_add_u32 s36, s36, 0x9000
	s_addc_u32 s37, s37, 0
	global_load_dword v68, v16, s[36:37] nt
	s_add_u32 s36, s36, 0x9000
	s_addc_u32 s37, s37, 0
	global_load_dword v69, v16, s[36:37] nt
	s_add_u32 s36, s36, 0x9000
	s_addc_u32 s37, s37, 0
	global_load_dword v70, v16, s[36:37] nt
	s_add_u32 s36, s36, 0x9000
	s_addc_u32 s37, s37, 0
	global_load_dword v71, v16, s[36:37] nt
	s_add_u32 s36, s36, 0x9000
	s_addc_u32 s37, s37, 0
	ds_read_b128 v[72:75], v37 offset:0
	ds_read_b128 v[76:79], v37 offset:16
	ds_read_b128 v[80:83], v37 offset:4096
	ds_read_b128 v[84:87], v37 offset:4112
	ds_read_b128 v[88:91], v37 offset:8192
	ds_read_b128 v[92:95], v37 offset:8208
	ds_read_b128 v[96:99], v37 offset:12288
	ds_read_b128 v[100:103], v37 offset:12304
	ds_read_b128 v[104:107], v37 offset:16384
	ds_read_b128 v[108:111], v37 offset:16400
	ds_read_b128 v[112:115], v37 offset:20480
	ds_read_b128 v[116:119], v37 offset:20496
	ds_read_b128 v[120:123], v37 offset:24576
	ds_read_b128 v[124:127], v37 offset:24592
	ds_read_b128 v[128:131], v37 offset:28672
	ds_read_b128 v[132:135], v37 offset:28688
	s_waitcnt vmcnt(24) lgkmcnt(0)
	v_fmac_f32_e32 v26, v72, v40
	v_fmac_f32_e32 v27, v80, v40
	v_fmac_f32_e32 v30, v88, v40
	v_fmac_f32_e32 v31, v96, v40
	v_fmac_f32_e32 v32, v104, v40
	v_fmac_f32_e32 v33, v112, v40
	v_fmac_f32_e32 v24, v120, v40
	v_fmac_f32_e32 v25, v128, v40
	v_fmac_f32_e32 v26, v73, v41
	v_fmac_f32_e32 v27, v81, v41
	v_fmac_f32_e32 v30, v89, v41
	v_fmac_f32_e32 v31, v97, v41
	v_fmac_f32_e32 v32, v105, v41
	v_fmac_f32_e32 v33, v113, v41
	v_fmac_f32_e32 v24, v121, v41
	v_fmac_f32_e32 v25, v129, v41
	v_fmac_f32_e32 v26, v74, v42
	v_fmac_f32_e32 v27, v82, v42
	v_fmac_f32_e32 v30, v90, v42
	v_fmac_f32_e32 v31, v98, v42
	v_fmac_f32_e32 v32, v106, v42
	v_fmac_f32_e32 v33, v114, v42
	v_fmac_f32_e32 v24, v122, v42
	v_fmac_f32_e32 v25, v130, v42
	v_fmac_f32_e32 v26, v75, v43
	v_fmac_f32_e32 v27, v83, v43
	v_fmac_f32_e32 v30, v91, v43
	v_fmac_f32_e32 v31, v99, v43
	v_fmac_f32_e32 v32, v107, v43
	v_fmac_f32_e32 v33, v115, v43
	v_fmac_f32_e32 v24, v123, v43
	v_fmac_f32_e32 v25, v131, v43
	v_fmac_f32_e32 v26, v76, v44
	v_fmac_f32_e32 v27, v84, v44
	v_fmac_f32_e32 v30, v92, v44
	v_fmac_f32_e32 v31, v100, v44
	v_fmac_f32_e32 v32, v108, v44
	v_fmac_f32_e32 v33, v116, v44
	v_fmac_f32_e32 v24, v124, v44
	v_fmac_f32_e32 v25, v132, v44
	v_fmac_f32_e32 v26, v77, v45
	v_fmac_f32_e32 v27, v85, v45
	v_fmac_f32_e32 v30, v93, v45
	v_fmac_f32_e32 v31, v101, v45
	v_fmac_f32_e32 v32, v109, v45
	v_fmac_f32_e32 v33, v117, v45
	v_fmac_f32_e32 v24, v125, v45
	v_fmac_f32_e32 v25, v133, v45
	v_fmac_f32_e32 v26, v78, v46
	v_fmac_f32_e32 v27, v86, v46
	v_fmac_f32_e32 v30, v94, v46
	v_fmac_f32_e32 v31, v102, v46
	v_fmac_f32_e32 v32, v110, v46
	v_fmac_f32_e32 v33, v118, v46
	v_fmac_f32_e32 v24, v126, v46
	v_fmac_f32_e32 v25, v134, v46
	v_fmac_f32_e32 v26, v79, v47
	v_fmac_f32_e32 v27, v87, v47
	v_fmac_f32_e32 v30, v95, v47
	v_fmac_f32_e32 v31, v103, v47
	v_fmac_f32_e32 v32, v111, v47
	v_fmac_f32_e32 v33, v119, v47
	v_fmac_f32_e32 v24, v127, v47
	v_fmac_f32_e32 v25, v135, v47
	ds_read_b128 v[72:75], v37 offset:32
	ds_read_b128 v[76:79], v37 offset:48
	ds_read_b128 v[80:83], v37 offset:4128
	ds_read_b128 v[84:87], v37 offset:4144
	ds_read_b128 v[88:91], v37 offset:8224
	ds_read_b128 v[92:95], v37 offset:8240
	ds_read_b128 v[96:99], v37 offset:12320
	ds_read_b128 v[100:103], v37 offset:12336
	ds_read_b128 v[104:107], v37 offset:16416
	ds_read_b128 v[108:111], v37 offset:16432
	ds_read_b128 v[112:115], v37 offset:20512
	ds_read_b128 v[116:119], v37 offset:20528
	ds_read_b128 v[120:123], v37 offset:24608
	ds_read_b128 v[124:127], v37 offset:24624
	ds_read_b128 v[128:131], v37 offset:28704
	ds_read_b128 v[132:135], v37 offset:28720
	s_waitcnt vmcnt(16) lgkmcnt(0)
	v_fmac_f32_e32 v26, v72, v48
	v_fmac_f32_e32 v27, v80, v48
	v_fmac_f32_e32 v30, v88, v48
	v_fmac_f32_e32 v31, v96, v48
	v_fmac_f32_e32 v32, v104, v48
	v_fmac_f32_e32 v33, v112, v48
	v_fmac_f32_e32 v24, v120, v48
	v_fmac_f32_e32 v25, v128, v48
	v_fmac_f32_e32 v26, v73, v49
	v_fmac_f32_e32 v27, v81, v49
	v_fmac_f32_e32 v30, v89, v49
	v_fmac_f32_e32 v31, v97, v49
	v_fmac_f32_e32 v32, v105, v49
	v_fmac_f32_e32 v33, v113, v49
	v_fmac_f32_e32 v24, v121, v49
	v_fmac_f32_e32 v25, v129, v49
	v_fmac_f32_e32 v26, v74, v50
	v_fmac_f32_e32 v27, v82, v50
	v_fmac_f32_e32 v30, v90, v50
	v_fmac_f32_e32 v31, v98, v50
	v_fmac_f32_e32 v32, v106, v50
	v_fmac_f32_e32 v33, v114, v50
	v_fmac_f32_e32 v24, v122, v50
	v_fmac_f32_e32 v25, v130, v50
	v_fmac_f32_e32 v26, v75, v51
	v_fmac_f32_e32 v27, v83, v51
	v_fmac_f32_e32 v30, v91, v51
	v_fmac_f32_e32 v31, v99, v51
	v_fmac_f32_e32 v32, v107, v51
	v_fmac_f32_e32 v33, v115, v51
	v_fmac_f32_e32 v24, v123, v51
	v_fmac_f32_e32 v25, v131, v51
	v_fmac_f32_e32 v26, v76, v52
	v_fmac_f32_e32 v27, v84, v52
	v_fmac_f32_e32 v30, v92, v52
	v_fmac_f32_e32 v31, v100, v52
	v_fmac_f32_e32 v32, v108, v52
	v_fmac_f32_e32 v33, v116, v52
	v_fmac_f32_e32 v24, v124, v52
	v_fmac_f32_e32 v25, v132, v52
	v_fmac_f32_e32 v26, v77, v53
	v_fmac_f32_e32 v27, v85, v53
	v_fmac_f32_e32 v30, v93, v53
	v_fmac_f32_e32 v31, v101, v53
	v_fmac_f32_e32 v32, v109, v53
	v_fmac_f32_e32 v33, v117, v53
	v_fmac_f32_e32 v24, v125, v53
	v_fmac_f32_e32 v25, v133, v53
	v_fmac_f32_e32 v26, v78, v54
	v_fmac_f32_e32 v27, v86, v54
	v_fmac_f32_e32 v30, v94, v54
	v_fmac_f32_e32 v31, v102, v54
	v_fmac_f32_e32 v32, v110, v54
	v_fmac_f32_e32 v33, v118, v54
	v_fmac_f32_e32 v24, v126, v54
	v_fmac_f32_e32 v25, v134, v54
	v_fmac_f32_e32 v26, v79, v55
	v_fmac_f32_e32 v27, v87, v55
	v_fmac_f32_e32 v30, v95, v55
	v_fmac_f32_e32 v31, v103, v55
	v_fmac_f32_e32 v32, v111, v55
	v_fmac_f32_e32 v33, v119, v55
	v_fmac_f32_e32 v24, v127, v55
	v_fmac_f32_e32 v25, v135, v55
	ds_read_b128 v[72:75], v37 offset:64
	ds_read_b128 v[76:79], v37 offset:80
	ds_read_b128 v[80:83], v37 offset:4160
	ds_read_b128 v[84:87], v37 offset:4176
	ds_read_b128 v[88:91], v37 offset:8256
	ds_read_b128 v[92:95], v37 offset:8272
	ds_read_b128 v[96:99], v37 offset:12352
	ds_read_b128 v[100:103], v37 offset:12368
	ds_read_b128 v[104:107], v37 offset:16448
	ds_read_b128 v[108:111], v37 offset:16464
	ds_read_b128 v[112:115], v37 offset:20544
	ds_read_b128 v[116:119], v37 offset:20560
	ds_read_b128 v[120:123], v37 offset:24640
	ds_read_b128 v[124:127], v37 offset:24656
	ds_read_b128 v[128:131], v37 offset:28736
	ds_read_b128 v[132:135], v37 offset:28752
	s_waitcnt vmcnt(8) lgkmcnt(0)
	v_fmac_f32_e32 v26, v72, v56
	v_fmac_f32_e32 v27, v80, v56
	v_fmac_f32_e32 v30, v88, v56
	v_fmac_f32_e32 v31, v96, v56
	v_fmac_f32_e32 v32, v104, v56
	v_fmac_f32_e32 v33, v112, v56
	v_fmac_f32_e32 v24, v120, v56
	v_fmac_f32_e32 v25, v128, v56
	v_fmac_f32_e32 v26, v73, v57
	v_fmac_f32_e32 v27, v81, v57
	v_fmac_f32_e32 v30, v89, v57
	v_fmac_f32_e32 v31, v97, v57
	v_fmac_f32_e32 v32, v105, v57
	v_fmac_f32_e32 v33, v113, v57
	v_fmac_f32_e32 v24, v121, v57
	v_fmac_f32_e32 v25, v129, v57
	v_fmac_f32_e32 v26, v74, v58
	v_fmac_f32_e32 v27, v82, v58
	v_fmac_f32_e32 v30, v90, v58
	v_fmac_f32_e32 v31, v98, v58
	v_fmac_f32_e32 v32, v106, v58
	v_fmac_f32_e32 v33, v114, v58
	v_fmac_f32_e32 v24, v122, v58
	v_fmac_f32_e32 v25, v130, v58
	v_fmac_f32_e32 v26, v75, v59
	v_fmac_f32_e32 v27, v83, v59
	v_fmac_f32_e32 v30, v91, v59
	v_fmac_f32_e32 v31, v99, v59
	v_fmac_f32_e32 v32, v107, v59
	v_fmac_f32_e32 v33, v115, v59
	v_fmac_f32_e32 v24, v123, v59
	v_fmac_f32_e32 v25, v131, v59
	v_fmac_f32_e32 v26, v76, v60
	v_fmac_f32_e32 v27, v84, v60
	v_fmac_f32_e32 v30, v92, v60
	v_fmac_f32_e32 v31, v100, v60
	v_fmac_f32_e32 v32, v108, v60
	v_fmac_f32_e32 v33, v116, v60
	v_fmac_f32_e32 v24, v124, v60
	v_fmac_f32_e32 v25, v132, v60
	v_fmac_f32_e32 v26, v77, v61
	v_fmac_f32_e32 v27, v85, v61
	v_fmac_f32_e32 v30, v93, v61
	v_fmac_f32_e32 v31, v101, v61
	v_fmac_f32_e32 v32, v109, v61
	v_fmac_f32_e32 v33, v117, v61
	v_fmac_f32_e32 v24, v125, v61
	v_fmac_f32_e32 v25, v133, v61
	v_fmac_f32_e32 v26, v78, v62
	v_fmac_f32_e32 v27, v86, v62
	v_fmac_f32_e32 v30, v94, v62
	v_fmac_f32_e32 v31, v102, v62
	v_fmac_f32_e32 v32, v110, v62
	v_fmac_f32_e32 v33, v118, v62
	v_fmac_f32_e32 v24, v126, v62
	v_fmac_f32_e32 v25, v134, v62
	v_fmac_f32_e32 v26, v79, v63
	v_fmac_f32_e32 v27, v87, v63
	v_fmac_f32_e32 v30, v95, v63
	v_fmac_f32_e32 v31, v103, v63
	v_fmac_f32_e32 v32, v111, v63
	v_fmac_f32_e32 v33, v119, v63
	v_fmac_f32_e32 v24, v127, v63
	v_fmac_f32_e32 v25, v135, v63
	ds_read_b128 v[72:75], v37 offset:96
	ds_read_b128 v[76:79], v37 offset:112
	ds_read_b128 v[80:83], v37 offset:4192
	ds_read_b128 v[84:87], v37 offset:4208
	ds_read_b128 v[88:91], v37 offset:8288
	ds_read_b128 v[92:95], v37 offset:8304
	ds_read_b128 v[96:99], v37 offset:12384
	ds_read_b128 v[100:103], v37 offset:12400
	ds_read_b128 v[104:107], v37 offset:16480
	ds_read_b128 v[108:111], v37 offset:16496
	ds_read_b128 v[112:115], v37 offset:20576
	ds_read_b128 v[116:119], v37 offset:20592
	ds_read_b128 v[120:123], v37 offset:24672
	ds_read_b128 v[124:127], v37 offset:24688
	ds_read_b128 v[128:131], v37 offset:28768
	ds_read_b128 v[132:135], v37 offset:28784
	s_waitcnt vmcnt(0) lgkmcnt(0)
	v_fmac_f32_e32 v26, v72, v64
	v_fmac_f32_e32 v27, v80, v64
	v_fmac_f32_e32 v30, v88, v64
	v_fmac_f32_e32 v31, v96, v64
	v_fmac_f32_e32 v32, v104, v64
	v_fmac_f32_e32 v33, v112, v64
	v_fmac_f32_e32 v24, v120, v64
	v_fmac_f32_e32 v25, v128, v64
	v_fmac_f32_e32 v26, v73, v65
	v_fmac_f32_e32 v27, v81, v65
	v_fmac_f32_e32 v30, v89, v65
	v_fmac_f32_e32 v31, v97, v65
	v_fmac_f32_e32 v32, v105, v65
	v_fmac_f32_e32 v33, v113, v65
	v_fmac_f32_e32 v24, v121, v65
	v_fmac_f32_e32 v25, v129, v65
	v_fmac_f32_e32 v26, v74, v66
	v_fmac_f32_e32 v27, v82, v66
	v_fmac_f32_e32 v30, v90, v66
	v_fmac_f32_e32 v31, v98, v66
	v_fmac_f32_e32 v32, v106, v66
	v_fmac_f32_e32 v33, v114, v66
	v_fmac_f32_e32 v24, v122, v66
	v_fmac_f32_e32 v25, v130, v66
	v_fmac_f32_e32 v26, v75, v67
	v_fmac_f32_e32 v27, v83, v67
	v_fmac_f32_e32 v30, v91, v67
	v_fmac_f32_e32 v31, v99, v67
	v_fmac_f32_e32 v32, v107, v67
	v_fmac_f32_e32 v33, v115, v67
	v_fmac_f32_e32 v24, v123, v67
	v_fmac_f32_e32 v25, v131, v67
	v_fmac_f32_e32 v26, v76, v68
	v_fmac_f32_e32 v27, v84, v68
	v_fmac_f32_e32 v30, v92, v68
	v_fmac_f32_e32 v31, v100, v68
	v_fmac_f32_e32 v32, v108, v68
	v_fmac_f32_e32 v33, v116, v68
	v_fmac_f32_e32 v24, v124, v68
	v_fmac_f32_e32 v25, v132, v68
	v_fmac_f32_e32 v26, v77, v69
	v_fmac_f32_e32 v27, v85, v69
	v_fmac_f32_e32 v30, v93, v69
	v_fmac_f32_e32 v31, v101, v69
	v_fmac_f32_e32 v32, v109, v69
	v_fmac_f32_e32 v33, v117, v69
	v_fmac_f32_e32 v24, v125, v69
	v_fmac_f32_e32 v25, v133, v69
	v_fmac_f32_e32 v26, v78, v70
	v_fmac_f32_e32 v27, v86, v70
	v_fmac_f32_e32 v30, v94, v70
	v_fmac_f32_e32 v31, v102, v70
	v_fmac_f32_e32 v32, v110, v70
	v_fmac_f32_e32 v33, v118, v70
	v_fmac_f32_e32 v24, v126, v70
	v_fmac_f32_e32 v25, v134, v70
	v_fmac_f32_e32 v26, v79, v71
	v_fmac_f32_e32 v27, v87, v71
	v_fmac_f32_e32 v30, v95, v71
	v_fmac_f32_e32 v31, v103, v71
	v_fmac_f32_e32 v32, v111, v71
	v_fmac_f32_e32 v33, v119, v71
	v_fmac_f32_e32 v24, v127, v71
	v_fmac_f32_e32 v25, v135, v71
	s_mov_b64 s[6:7], exec
	s_or_b64 exec, exec, s[6:7]
	s_mul_i32 s0, s12, 0xffffff70
	s_add_i32 s0, s0, s8
	s_lshl_b32 s0, s0, 6
	v_readlane_b32 s16, v253, 11
	s_ashr_i32 s1, s0, 31
	s_mul_i32 s7, s12, 0x9000
	v_readlane_b32 s22, v253, 17
	s_mul_hi_i32 s6, s12, 0x9000
	v_readlane_b32 s23, v253, 18
	s_add_u32 s7, s22, s7
	s_addc_u32 s13, s23, s6
	s_lshl_b64 s[0:1], s[0:1], 2
	s_add_u32 s6, s7, s0
	s_addc_u32 s7, s13, s1
	ds_write2st64_b32 v34, v26, v27 offset0:128 offset1:129
	ds_write2st64_b32 v34, v30, v31 offset0:130 offset1:131
	ds_write2st64_b32 v34, v32, v33 offset0:132 offset1:133
	ds_write2st64_b32 v34, v24, v25 offset0:134 offset1:135
	s_waitcnt lgkmcnt(0)
	s_barrier
	global_load_dword v6, v16, s[6:7]
	ds_read2st64_b32 v[2:3], v19 offset0:128 offset1:136
	ds_read2st64_b32 v[4:5], v19 offset0:144 offset1:152
	s_lshl_b32 s12, s12, 3
	s_add_i32 s8, s8, s52
	s_add_i32 s9, s9, s10
	s_waitcnt lgkmcnt(1)
	v_add_f32_e32 v7, v2, v3
	s_waitcnt lgkmcnt(0)
	v_add_f32_e32 v4, v7, v4
	v_lshl_add_u64 v[2:3], v[20:21], 0, s[0:1]
	v_add_f32_e32 v7, v4, v5
	v_or_b32_e32 v4, s12, v14
	v_mad_i64_i32 v[4:5], s[0:1], v4, s11, v[2:3]
	s_cmpk_gt_i32 s8, 0x23f
	v_readlane_b32 s17, v253, 12
	v_readlane_b32 s18, v253, 13
	v_readlane_b32 s19, v253, 14
	v_readlane_b32 s20, v253, 15
	v_readlane_b32 s21, v253, 16
	v_readlane_b32 s24, v253, 19
	v_readlane_b32 s25, v253, 20
	v_readlane_b32 s26, v253, 21
	v_readlane_b32 s27, v253, 22
	v_readlane_b32 s28, v253, 23
	v_readlane_b32 s29, v253, 24
	v_readlane_b32 s30, v253, 25
	v_readlane_b32 s31, v253, 26
	s_waitcnt vmcnt(0)
	v_add_f32_e32 v6, v7, v6
	global_store_dword v[4:5], v6, off
	global_load_dword v8, v16, s[6:7]
	ds_read2st64_b32 v[4:5], v35 offset0:128 offset1:136
	ds_read2st64_b32 v[6:7], v35 offset0:144 offset1:152
	s_waitcnt lgkmcnt(1)
	v_add_f32_e32 v4, v4, v5
	s_waitcnt lgkmcnt(0)
	v_add_f32_e32 v4, v4, v6
	v_add_f32_e32 v4, v4, v7
	v_or_b32_e32 v5, s12, v18
	v_mad_i64_i32 v[2:3], s[0:1], v5, s11, v[2:3]
	s_waitcnt vmcnt(0)
	v_add_f32_e32 v4, v4, v8
	global_store_dword v[2:3], v4, off
	s_barrier
	s_cbranch_scc0 .LBB0_11
